# BM selected-attention: waves 4-7 sleep 256 cycles before entering the block loop so the two waves of a SIMD run half a pair out of phase
# speedup vs baseline: 1.0067x; 1.0067x over previous
.LBB0_1549:
.LBB0_1550:
	v_readfirstlane_b32 s46, v70
	v_readfirstlane_b32 s47, v71
	v_readfirstlane_b32 s62, v72
	v_readfirstlane_b32 s63, v73
	v_and_b32_e32 v248, 15, v181
	v_lshrrev_b32_e32 v249, 4, v181
	v_lshrrev_b32_e32 v248, 2, v248
	v_lshlrev_b32_e32 v249, 2, v249
	v_readlane_b32 s23, v243, 32
	v_mov_b32_e32 v244, 1
	v_lshlrev_b32_e32 v244, v248, v244
	s_mov_b32 s16, 0x3e38aa3b
	s_mov_b32 s17, 0x3e38aa3b
	v_lshlrev_b32_e32 v79, 4, v181
	s_add_i32 s23, s23, s97
	v_add_u32_e32 v247, s23, v248
	v_mad_u64_u32 v[250:251], s[50:51], v247, v212, v[68:69]
	global_load_dwordx4 v[100:103], v[250:251], off
	global_load_dwordx4 v[104:107], v[250:251], off offset:64
	v_add_u32_e32 v249, 4, v247
	v_mad_u64_u32 v[250:251], s[50:51], v249, v212, v[68:69]
	global_load_dwordx4 v[108:111], v[250:251], off
	global_load_dwordx4 v[112:115], v[250:251], off offset:64
	v_add_u32_e32 v249, 8, v247
	v_mad_u64_u32 v[250:251], s[50:51], v249, v212, v[68:69]
	global_load_dwordx4 v[116:119], v[250:251], off
	global_load_dwordx4 v[120:123], v[250:251], off offset:64
	v_add_u32_e32 v249, 12, v247
	v_mad_u64_u32 v[250:251], s[50:51], v249, v212, v[68:69]
	global_load_dwordx4 v[124:127], v[250:251], off
	global_load_dwordx4 v[128:131], v[250:251], off offset:64
	v_and_b32_e32 v248, 15, v181
	v_lshrrev_b32_e32 v249, 4, v181
	v_lshlrev_b32_e32 v198, 6, v248
	v_lshl_add_u32 v198, v249, 2, v198
	v_add_u32_e32 v198, s96, v198
	v_lshl_add_u32 v199, v248, 2, s96
	ds_read_b32 v12, v198 offset:16384
	ds_read_b32 v13, v198 offset:16400
	ds_read_b32 v14, v198 offset:16416
	ds_read_b32 v15, v198 offset:16432
	ds_read_b32 v16, v199 offset:17408
	v_lshl_add_u32 v199, v181, 2, s96
	v_mov_b32_e32 v17, 1
	v_lshlrev_b32_e32 v17, v248, v17
	s_waitcnt lgkmcnt(0)
	v_mul_f32_e32 v81, 0x3fb8aa3b, v81
	ds_write_b32 v199, v11 offset:16384
	ds_write_b32 v199, v11 offset:16640
	ds_write_b32 v199, v11 offset:16896
	ds_write_b32 v199, v11 offset:17152
	v_cmp_lt_i32_e32 vcc, v249, v16
	v_and_b32_e32 v12, 0xff, v12
	v_lshl_add_u32 v12, v12, 2, s96
	v_cndmask_b32_e32 v18, 0, v17, vcc
	ds_or_b32 v12, v18 offset:16384
	v_add_u32_e32 v18, 4, v249
	v_cmp_lt_i32_e32 vcc, v18, v16
	v_and_b32_e32 v13, 0xff, v13
	v_lshl_add_u32 v13, v13, 2, s96
	v_cndmask_b32_e32 v18, 0, v17, vcc
	ds_or_b32 v13, v18 offset:16384
	v_add_u32_e32 v18, 8, v249
	v_cmp_lt_i32_e32 vcc, v18, v16
	v_and_b32_e32 v14, 0xff, v14
	v_lshl_add_u32 v14, v14, 2, s96
	v_cndmask_b32_e32 v18, 0, v17, vcc
	ds_or_b32 v14, v18 offset:16384
	v_add_u32_e32 v18, 12, v249
	v_cmp_lt_i32_e32 vcc, v18, v16
	v_and_b32_e32 v15, 0xff, v15
	v_lshl_add_u32 v15, v15, 2, s96
	v_cndmask_b32_e32 v18, 0, v17, vcc
	ds_or_b32 v15, v18 offset:16384
	s_waitcnt lgkmcnt(0)
	ds_read_b32 v12, v199 offset:16384
	ds_read_b32 v13, v199 offset:16640
	ds_read_b32 v14, v199 offset:16896
	ds_read_b32 v15, v199 offset:17152
	s_mov_b32 s25, 0
	s_waitcnt lgkmcnt(0)
	v_cmp_ne_u32_e64 s[4:5], 0, v12
	v_lshlrev_b32_e32 v16, 16, v12
	v_add_u32_e32 v17, 0, v181
	v_or_b32_e32 v16, v16, v17
	v_mbcnt_lo_u32_b32 v17, s4, 0
	v_mbcnt_hi_u32_b32 v17, s5, v17
	v_add_u32_e32 v17, s25, v17
	v_lshl_add_u32 v17, v17, 2, s96
	v_add_u32_e32 v17, 0x4000, v17
	v_add_u32_e32 v18, 0x4400, v199
	s_bcnt1_i32_b64 s13, s[4:5]
	v_cndmask_b32_e64 v17, v18, v17, s[4:5]
	s_add_i32 s25, s25, s13
	ds_write_b32 v17, v16
	v_cmp_ne_u32_e64 s[4:5], 0, v13
	v_lshlrev_b32_e32 v16, 16, v13
	v_add_u32_e32 v17, 64, v181
	v_or_b32_e32 v16, v16, v17
	v_mbcnt_lo_u32_b32 v17, s4, 0
	v_mbcnt_hi_u32_b32 v17, s5, v17
	v_add_u32_e32 v17, s25, v17
	v_lshl_add_u32 v17, v17, 2, s96
	v_add_u32_e32 v17, 0x4000, v17
	v_add_u32_e32 v18, 0x4400, v199
	s_bcnt1_i32_b64 s13, s[4:5]
	v_cndmask_b32_e64 v17, v18, v17, s[4:5]
	s_add_i32 s25, s25, s13
	ds_write_b32 v17, v16
	v_cmp_ne_u32_e64 s[4:5], 0, v14
	v_lshlrev_b32_e32 v16, 16, v14
	v_add_u32_e32 v17, 128, v181
	v_or_b32_e32 v16, v16, v17
	v_mbcnt_lo_u32_b32 v17, s4, 0
	v_mbcnt_hi_u32_b32 v17, s5, v17
	v_add_u32_e32 v17, s25, v17
	v_lshl_add_u32 v17, v17, 2, s96
	v_add_u32_e32 v17, 0x4000, v17
	v_add_u32_e32 v18, 0x4400, v199
	s_bcnt1_i32_b64 s13, s[4:5]
	v_cndmask_b32_e64 v17, v18, v17, s[4:5]
	s_add_i32 s25, s25, s13
	ds_write_b32 v17, v16
	v_cmp_ne_u32_e64 s[4:5], 0, v15
	v_lshlrev_b32_e32 v16, 16, v15
	v_add_u32_e32 v17, 192, v181
	v_or_b32_e32 v16, v16, v17
	v_mbcnt_lo_u32_b32 v17, s4, 0
	v_mbcnt_hi_u32_b32 v17, s5, v17
	v_add_u32_e32 v17, s25, v17
	v_lshl_add_u32 v17, v17, 2, s96
	v_add_u32_e32 v17, 0x4000, v17
	v_add_u32_e32 v18, 0x4400, v199
	s_bcnt1_i32_b64 s13, s[4:5]
	v_cndmask_b32_e64 v17, v18, v17, s[4:5]
	s_add_i32 s25, s25, s13
	ds_write_b32 v17, v16
	s_waitcnt vmcnt(0)
	v_lshlrev_b32_e32 v245, 16, v100
	v_and_b32_e32 v246, 0xffff0000, v100
	v_mul_f32_e32 v245, 0x41000000, v245
	v_mul_f32_e32 v246, 0x41000000, v246
	v_lshlrev_b32_e32 v248, 16, v101
	v_and_b32_e32 v249, 0xffff0000, v101
	v_cvt_pk_fp8_f32 v164, v245, v246
	v_mul_f32_e32 v248, 0x41000000, v248
	v_mul_f32_e32 v249, 0x41000000, v249
	s_nop 0
	v_cvt_pk_fp8_f32 v164, v248, v249 op_sel:[0,0,1]
	v_lshlrev_b32_e32 v245, 16, v102
	v_and_b32_e32 v246, 0xffff0000, v102
	v_mul_f32_e32 v245, 0x41000000, v245
	v_mul_f32_e32 v246, 0x41000000, v246
	v_lshlrev_b32_e32 v248, 16, v103
	v_and_b32_e32 v249, 0xffff0000, v103
	v_cvt_pk_fp8_f32 v165, v245, v246
	v_mul_f32_e32 v248, 0x41000000, v248
	v_mul_f32_e32 v249, 0x41000000, v249
	s_nop 0
	v_cvt_pk_fp8_f32 v165, v248, v249 op_sel:[0,0,1]
	v_lshlrev_b32_e32 v245, 16, v104
	v_and_b32_e32 v246, 0xffff0000, v104
	v_mul_f32_e32 v245, 0x41000000, v245
	v_mul_f32_e32 v246, 0x41000000, v246
	v_lshlrev_b32_e32 v248, 16, v105
	v_and_b32_e32 v249, 0xffff0000, v105
	v_cvt_pk_fp8_f32 v166, v245, v246
	v_mul_f32_e32 v248, 0x41000000, v248
	v_mul_f32_e32 v249, 0x41000000, v249
	s_nop 0
	v_cvt_pk_fp8_f32 v166, v248, v249 op_sel:[0,0,1]
	v_lshlrev_b32_e32 v245, 16, v106
	v_and_b32_e32 v246, 0xffff0000, v106
	v_mul_f32_e32 v245, 0x41000000, v245
	v_mul_f32_e32 v246, 0x41000000, v246
	v_lshlrev_b32_e32 v248, 16, v107
	v_and_b32_e32 v249, 0xffff0000, v107
	v_cvt_pk_fp8_f32 v167, v245, v246
	v_mul_f32_e32 v248, 0x41000000, v248
	v_mul_f32_e32 v249, 0x41000000, v249
	s_nop 0
	v_cvt_pk_fp8_f32 v167, v248, v249 op_sel:[0,0,1]
	v_lshlrev_b32_e32 v245, 16, v108
	v_and_b32_e32 v246, 0xffff0000, v108
	v_mul_f32_e32 v245, 0x41000000, v245
	v_mul_f32_e32 v246, 0x41000000, v246
	v_lshlrev_b32_e32 v248, 16, v109
	v_and_b32_e32 v249, 0xffff0000, v109
	v_cvt_pk_fp8_f32 v168, v245, v246
	v_mul_f32_e32 v248, 0x41000000, v248
	v_mul_f32_e32 v249, 0x41000000, v249
	s_nop 0
	v_cvt_pk_fp8_f32 v168, v248, v249 op_sel:[0,0,1]
	v_lshlrev_b32_e32 v245, 16, v110
	v_and_b32_e32 v246, 0xffff0000, v110
	v_mul_f32_e32 v245, 0x41000000, v245
	v_mul_f32_e32 v246, 0x41000000, v246
	v_lshlrev_b32_e32 v248, 16, v111
	v_and_b32_e32 v249, 0xffff0000, v111
	v_cvt_pk_fp8_f32 v169, v245, v246
	v_mul_f32_e32 v248, 0x41000000, v248
	v_mul_f32_e32 v249, 0x41000000, v249
	s_nop 0
	v_cvt_pk_fp8_f32 v169, v248, v249 op_sel:[0,0,1]
	v_lshlrev_b32_e32 v245, 16, v112
	v_and_b32_e32 v246, 0xffff0000, v112
	v_mul_f32_e32 v245, 0x41000000, v245
	v_mul_f32_e32 v246, 0x41000000, v246
	v_lshlrev_b32_e32 v248, 16, v113
	v_and_b32_e32 v249, 0xffff0000, v113
	v_cvt_pk_fp8_f32 v170, v245, v246
	v_mul_f32_e32 v248, 0x41000000, v248
	v_mul_f32_e32 v249, 0x41000000, v249
	s_nop 0
	v_cvt_pk_fp8_f32 v170, v248, v249 op_sel:[0,0,1]
	v_lshlrev_b32_e32 v245, 16, v114
	v_and_b32_e32 v246, 0xffff0000, v114
	v_mul_f32_e32 v245, 0x41000000, v245
	v_mul_f32_e32 v246, 0x41000000, v246
	v_lshlrev_b32_e32 v248, 16, v115
	v_and_b32_e32 v249, 0xffff0000, v115
	v_cvt_pk_fp8_f32 v171, v245, v246
	v_mul_f32_e32 v248, 0x41000000, v248
	v_mul_f32_e32 v249, 0x41000000, v249
	s_nop 0
	v_cvt_pk_fp8_f32 v171, v248, v249 op_sel:[0,0,1]
	v_lshlrev_b32_e32 v245, 16, v116
	v_and_b32_e32 v246, 0xffff0000, v116
	v_mul_f32_e32 v245, 0x41000000, v245
	v_mul_f32_e32 v246, 0x41000000, v246
	v_lshlrev_b32_e32 v248, 16, v117
	v_and_b32_e32 v249, 0xffff0000, v117
	v_cvt_pk_fp8_f32 v182, v245, v246
	v_mul_f32_e32 v248, 0x41000000, v248
	v_mul_f32_e32 v249, 0x41000000, v249
	s_nop 0
	v_cvt_pk_fp8_f32 v182, v248, v249 op_sel:[0,0,1]
	v_lshlrev_b32_e32 v245, 16, v118
	v_and_b32_e32 v246, 0xffff0000, v118
	v_mul_f32_e32 v245, 0x41000000, v245
	v_mul_f32_e32 v246, 0x41000000, v246
	v_lshlrev_b32_e32 v248, 16, v119
	v_and_b32_e32 v249, 0xffff0000, v119
	v_cvt_pk_fp8_f32 v183, v245, v246
	v_mul_f32_e32 v248, 0x41000000, v248
	v_mul_f32_e32 v249, 0x41000000, v249
	s_nop 0
	v_cvt_pk_fp8_f32 v183, v248, v249 op_sel:[0,0,1]
	v_lshlrev_b32_e32 v245, 16, v120
	v_and_b32_e32 v246, 0xffff0000, v120
	v_mul_f32_e32 v245, 0x41000000, v245
	v_mul_f32_e32 v246, 0x41000000, v246
	v_lshlrev_b32_e32 v248, 16, v121
	v_and_b32_e32 v249, 0xffff0000, v121
	v_cvt_pk_fp8_f32 v184, v245, v246
	v_mul_f32_e32 v248, 0x41000000, v248
	v_mul_f32_e32 v249, 0x41000000, v249
	s_nop 0
	v_cvt_pk_fp8_f32 v184, v248, v249 op_sel:[0,0,1]
	v_lshlrev_b32_e32 v245, 16, v122
	v_and_b32_e32 v246, 0xffff0000, v122
	v_mul_f32_e32 v245, 0x41000000, v245
	v_mul_f32_e32 v246, 0x41000000, v246
	v_lshlrev_b32_e32 v248, 16, v123
	v_and_b32_e32 v249, 0xffff0000, v123
	v_cvt_pk_fp8_f32 v185, v245, v246
	v_mul_f32_e32 v248, 0x41000000, v248
	v_mul_f32_e32 v249, 0x41000000, v249
	s_nop 0
	v_cvt_pk_fp8_f32 v185, v248, v249 op_sel:[0,0,1]
	v_lshlrev_b32_e32 v245, 16, v124
	v_and_b32_e32 v246, 0xffff0000, v124
	v_mul_f32_e32 v245, 0x41000000, v245
	v_mul_f32_e32 v246, 0x41000000, v246
	v_lshlrev_b32_e32 v248, 16, v125
	v_and_b32_e32 v249, 0xffff0000, v125
	v_cvt_pk_fp8_f32 v186, v245, v246
	v_mul_f32_e32 v248, 0x41000000, v248
	v_mul_f32_e32 v249, 0x41000000, v249
	s_nop 0
	v_cvt_pk_fp8_f32 v186, v248, v249 op_sel:[0,0,1]
	v_lshlrev_b32_e32 v245, 16, v126
	v_and_b32_e32 v246, 0xffff0000, v126
	v_mul_f32_e32 v245, 0x41000000, v245
	v_mul_f32_e32 v246, 0x41000000, v246
	v_lshlrev_b32_e32 v248, 16, v127
	v_and_b32_e32 v249, 0xffff0000, v127
	v_cvt_pk_fp8_f32 v187, v245, v246
	v_mul_f32_e32 v248, 0x41000000, v248
	v_mul_f32_e32 v249, 0x41000000, v249
	s_nop 0
	v_cvt_pk_fp8_f32 v187, v248, v249 op_sel:[0,0,1]
	v_lshlrev_b32_e32 v245, 16, v128
	v_and_b32_e32 v246, 0xffff0000, v128
	v_mul_f32_e32 v245, 0x41000000, v245
	v_mul_f32_e32 v246, 0x41000000, v246
	v_lshlrev_b32_e32 v248, 16, v129
	v_and_b32_e32 v249, 0xffff0000, v129
	v_cvt_pk_fp8_f32 v188, v245, v246
	v_mul_f32_e32 v248, 0x41000000, v248
	v_mul_f32_e32 v249, 0x41000000, v249
	s_nop 0
	v_cvt_pk_fp8_f32 v188, v248, v249 op_sel:[0,0,1]
	v_lshlrev_b32_e32 v245, 16, v130
	v_and_b32_e32 v246, 0xffff0000, v130
	v_mul_f32_e32 v245, 0x41000000, v245
	v_mul_f32_e32 v246, 0x41000000, v246
	v_lshlrev_b32_e32 v248, 16, v131
	v_and_b32_e32 v249, 0xffff0000, v131
	v_cvt_pk_fp8_f32 v189, v245, v246
	v_mul_f32_e32 v248, 0x41000000, v248
	v_mul_f32_e32 v249, 0x41000000, v249
	s_nop 0
	v_cvt_pk_fp8_f32 v189, v248, v249 op_sel:[0,0,1]
	v_mov_b64_e32 v[100:101], 0
	v_mov_b64_e32 v[102:103], 0
	v_mov_b64_e32 v[104:105], 0
	v_mov_b64_e32 v[106:107], 0
	v_mov_b64_e32 v[108:109], 0
	v_mov_b64_e32 v[110:111], 0
	v_mov_b64_e32 v[112:113], 0
	v_mov_b64_e32 v[114:115], 0
	v_mov_b32_e32 v190, 0
	v_mov_b32_e32 v194, 0
	v_mov_b64_e32 v[116:117], 0
	v_mov_b64_e32 v[118:119], 0
	v_mov_b64_e32 v[120:121], 0
	v_mov_b64_e32 v[122:123], 0
	v_mov_b64_e32 v[124:125], 0
	v_mov_b64_e32 v[126:127], 0
	v_mov_b64_e32 v[128:129], 0
	v_mov_b64_e32 v[130:131], 0
	v_mov_b32_e32 v191, 0
	v_mov_b32_e32 v195, 0
	v_mov_b64_e32 v[132:133], 0
	v_mov_b64_e32 v[134:135], 0
	v_mov_b64_e32 v[136:137], 0
	v_mov_b64_e32 v[138:139], 0
	v_mov_b64_e32 v[140:141], 0
	v_mov_b64_e32 v[142:143], 0
	v_mov_b64_e32 v[144:145], 0
	v_mov_b64_e32 v[146:147], 0
	v_mov_b32_e32 v192, 0
	v_mov_b32_e32 v196, 0
	v_mov_b64_e32 v[148:149], 0
	v_mov_b64_e32 v[150:151], 0
	v_mov_b64_e32 v[152:153], 0
	v_mov_b64_e32 v[154:155], 0
	v_mov_b64_e32 v[156:157], 0
	v_mov_b64_e32 v[158:159], 0
	v_mov_b64_e32 v[160:161], 0
	v_mov_b64_e32 v[162:163], 0
	v_mov_b32_e32 v193, 0
	v_mov_b32_e32 v197, 0
	v_mov_b32_e32 v77, 0xff800000
	v_mov_b32_e32 v78, 0xff800000
	s_waitcnt lgkmcnt(0)
	s_mov_b32 s35, 0
	s_lshl_b32 s13, s35, 2
	s_add_i32 s13, s13, s96
	v_mov_b32_e32 v76, s13
	ds_read_b32 v76, v76 offset:16384
	s_add_i32 s14, s25, -1
	s_min_i32 s14, s14, 1
	s_waitcnt lgkmcnt(0)
	v_readfirstlane_b32 s13, v76
	s_and_b32 s54, s13, 0xffff
	s_lshr_b32 s48, s13, 16
	s_lshl_b32 s13, s14, 2
	s_add_i32 s13, s13, s96
	v_mov_b32_e32 v76, s13
	ds_read_b32 v76, v76 offset:16384
	s_lshl_b32 s12, s54, 12
	s_add_u32 s30, s46, s12
	s_addc_u32 s31, s47, 0
	global_load_dwordx4 v[2:5], v79, s[30:31]
	global_load_dwordx4 v[6:9], v79, s[30:31] offset:1024
	global_load_dwordx4 v[12:15], v79, s[30:31] offset:2048
	global_load_dwordx4 v[16:19], v79, s[30:31] offset:3072
	s_lshl_b32 s12, s54, 12
	s_add_u32 s30, s62, s12
	s_addc_u32 s31, s63, 0
	global_load_dwordx4 v[36:39], v79, s[30:31]
	global_load_dwordx4 v[40:43], v79, s[30:31] offset:1024
	global_load_dwordx4 v[44:47], v79, s[30:31] offset:2048
	global_load_dwordx4 v[48:51], v79, s[30:31] offset:3072
	s_waitcnt lgkmcnt(0)
	v_readfirstlane_b32 s13, v76
	s_and_b32 s15, s13, 0xffff
	s_lshr_b32 s27, s13, 16
	v_readfirstlane_b32 s83, v1
	s_bitcmp1_b32 s83, 8
	s_cbranch_scc0 .Lbm2_nostag
	s_sleep 4
.Lbm2_nostag:
.Lbm2_blkA:
	s_lshl_b32 s12, s15, 12
	s_add_u32 s30, s46, s12
	s_addc_u32 s31, s47, 0
	global_load_dwordx4 v[20:23], v79, s[30:31]
	global_load_dwordx4 v[24:27], v79, s[30:31] offset:1024
	global_load_dwordx4 v[28:31], v79, s[30:31] offset:2048
	global_load_dwordx4 v[32:35], v79, s[30:31] offset:3072
	s_lshl_b32 s12, s15, 12
	s_add_u32 s30, s62, s12
	s_addc_u32 s31, s63, 0
	global_load_dwordx4 v[52:55], v79, s[30:31]
	global_load_dwordx4 v[56:59], v79, s[30:31] offset:1024
	global_load_dwordx4 v[60:63], v79, s[30:31] offset:2048
	global_load_dwordx4 v[64:67], v79, s[30:31] offset:3072
	s_add_i32 s14, s35, 2
	s_add_i32 s13, s25, -1
	s_min_i32 s14, s14, s13
	s_lshl_b32 s13, s14, 2
	s_add_i32 s13, s13, s96
	v_mov_b32_e32 v76, s13
	ds_read_b32 v76, v76 offset:16384
	s_cmp_ge_i32 s54, s21
	s_cselect_b32 s14, 1, 0
	s_bfe_u32 s29, s48, 0x40000
	s_cmp_eq_u32 s29, 0
	s_cbranch_scc1 .Lbm2_Ag0_skip
	s_waitcnt vmcnt(12)
	v_mfma_f32_16x16x32_fp8_fp8 v[84:87], v[2:3], v[164:165], 0
	v_mfma_f32_16x16x32_fp8_fp8 v[88:91], v[6:7], v[164:165], 0
	v_mfma_f32_16x16x32_fp8_fp8 v[92:95], v[12:13], v[164:165], 0
	v_mfma_f32_16x16x32_fp8_fp8 v[96:99], v[16:17], v[164:165], 0
	v_mfma_f32_16x16x32_fp8_fp8 v[84:87], v[4:5], v[166:167], v[84:87]
	v_mfma_f32_16x16x32_fp8_fp8 v[88:91], v[8:9], v[166:167], v[88:91]
	v_mfma_f32_16x16x32_fp8_fp8 v[92:95], v[14:15], v[166:167], v[92:95]
	v_mfma_f32_16x16x32_fp8_fp8 v[96:99], v[18:19], v[166:167], v[96:99]
	v_and_b32_e32 v199, s29, v244
	s_cmp_eq_u32 s14, 1
	v_cmp_ne_u32_e32 vcc, 0, v199
	s_cbranch_scc1 .Lbm2_Ag0_near
	v_add_f32_e32 v200, v81, v190
	v_cndmask_b32_e32 v200, v77, v200, vcc
	v_pk_fma_f32 v[84:85], v[84:85], s[16:17], v[200:201] op_sel_hi:[1,1,0]
	v_pk_fma_f32 v[86:87], v[86:87], s[16:17], v[200:201] op_sel_hi:[1,1,0]
	v_pk_fma_f32 v[88:89], v[88:89], s[16:17], v[200:201] op_sel_hi:[1,1,0]
	v_pk_fma_f32 v[90:91], v[90:91], s[16:17], v[200:201] op_sel_hi:[1,1,0]
	v_pk_fma_f32 v[92:93], v[92:93], s[16:17], v[200:201] op_sel_hi:[1,1,0]
	v_pk_fma_f32 v[94:95], v[94:95], s[16:17], v[200:201] op_sel_hi:[1,1,0]
	v_pk_fma_f32 v[96:97], v[96:97], s[16:17], v[200:201] op_sel_hi:[1,1,0]
	v_pk_fma_f32 v[98:99], v[98:99], s[16:17], v[200:201] op_sel_hi:[1,1,0]

.LBB0_2049:
.LBB0_2050:
	v_readfirstlane_b32 s40, v70
	v_readfirstlane_b32 s41, v71
	v_readfirstlane_b32 s62, v72
	v_readfirstlane_b32 s63, v73
	v_and_b32_e32 v248, 15, v181
	v_lshrrev_b32_e32 v249, 4, v181
	v_lshrrev_b32_e32 v248, 2, v248
	v_lshlrev_b32_e32 v249, 2, v249
	v_readlane_b32 s23, v243, 32
	v_mov_b32_e32 v244, 1
	v_lshlrev_b32_e32 v244, v248, v244
	s_mov_b32 s10, 0x3e38aa3b
	s_mov_b32 s11, 0x3e38aa3b
	v_lshlrev_b32_e32 v79, 4, v181
	s_add_i32 s23, s23, s47
	v_add_u32_e32 v247, s23, v248
	v_mad_u64_u32 v[250:251], s[6:7], v247, v212, v[68:69]
	global_load_dwordx4 v[100:103], v[250:251], off
	global_load_dwordx4 v[104:107], v[250:251], off offset:64
	v_add_u32_e32 v249, 4, v247
	v_mad_u64_u32 v[250:251], s[6:7], v249, v212, v[68:69]
	global_load_dwordx4 v[108:111], v[250:251], off
	global_load_dwordx4 v[112:115], v[250:251], off offset:64
	v_add_u32_e32 v249, 8, v247
	v_mad_u64_u32 v[250:251], s[6:7], v249, v212, v[68:69]
	global_load_dwordx4 v[116:119], v[250:251], off
	global_load_dwordx4 v[120:123], v[250:251], off offset:64
	v_add_u32_e32 v249, 12, v247
	v_mad_u64_u32 v[250:251], s[6:7], v249, v212, v[68:69]
	global_load_dwordx4 v[124:127], v[250:251], off
	global_load_dwordx4 v[128:131], v[250:251], off offset:64
	v_and_b32_e32 v248, 15, v181
	v_lshrrev_b32_e32 v249, 4, v181
	v_lshlrev_b32_e32 v198, 6, v248
	v_lshl_add_u32 v198, v249, 2, v198
	v_add_u32_e32 v198, s46, v198
	v_lshl_add_u32 v199, v248, 2, s46
	ds_read_b32 v12, v198 offset:16384
	ds_read_b32 v13, v198 offset:16400
	ds_read_b32 v14, v198 offset:16416
	ds_read_b32 v15, v198 offset:16432
	ds_read_b32 v16, v199 offset:17408
	v_lshl_add_u32 v199, v181, 2, s46
	v_mov_b32_e32 v17, 1
	v_lshlrev_b32_e32 v17, v248, v17
	s_waitcnt lgkmcnt(0)
	v_mul_f32_e32 v81, 0x3fb8aa3b, v81
	ds_write_b32 v199, v11 offset:16384
	ds_write_b32 v199, v11 offset:16640
	ds_write_b32 v199, v11 offset:16896
	ds_write_b32 v199, v11 offset:17152
	v_cmp_lt_i32_e32 vcc, v249, v16
	v_and_b32_e32 v12, 0xff, v12
	v_lshl_add_u32 v12, v12, 2, s46
	v_cndmask_b32_e32 v18, 0, v17, vcc
	ds_or_b32 v12, v18 offset:16384
	v_add_u32_e32 v18, 4, v249
	v_cmp_lt_i32_e32 vcc, v18, v16
	v_and_b32_e32 v13, 0xff, v13
	v_lshl_add_u32 v13, v13, 2, s46
	v_cndmask_b32_e32 v18, 0, v17, vcc
	ds_or_b32 v13, v18 offset:16384
	v_add_u32_e32 v18, 8, v249
	v_cmp_lt_i32_e32 vcc, v18, v16
	v_and_b32_e32 v14, 0xff, v14
	v_lshl_add_u32 v14, v14, 2, s46
	v_cndmask_b32_e32 v18, 0, v17, vcc
	ds_or_b32 v14, v18 offset:16384
	v_add_u32_e32 v18, 12, v249
	v_cmp_lt_i32_e32 vcc, v18, v16
	v_and_b32_e32 v15, 0xff, v15
	v_lshl_add_u32 v15, v15, 2, s46
	v_cndmask_b32_e32 v18, 0, v17, vcc
	ds_or_b32 v15, v18 offset:16384
	s_waitcnt lgkmcnt(0)
	ds_read_b32 v12, v199 offset:16384
	ds_read_b32 v13, v199 offset:16640
	ds_read_b32 v14, v199 offset:16896
	ds_read_b32 v15, v199 offset:17152
	s_mov_b32 s25, 0
	s_waitcnt lgkmcnt(0)
	v_cmp_ne_u32_e64 s[4:5], 0, v12
	v_lshlrev_b32_e32 v16, 16, v12
	v_add_u32_e32 v17, 0, v181
	v_or_b32_e32 v16, v16, v17
	v_mbcnt_lo_u32_b32 v17, s4, 0
	v_mbcnt_hi_u32_b32 v17, s5, v17
	v_add_u32_e32 v17, s25, v17
	v_lshl_add_u32 v17, v17, 2, s46
	v_add_u32_e32 v17, 0x4000, v17
	v_add_u32_e32 v18, 0x4400, v199
	s_bcnt1_i32_b64 s9, s[4:5]
	v_cndmask_b32_e64 v17, v18, v17, s[4:5]
	s_add_i32 s25, s25, s9
	ds_write_b32 v17, v16
	v_cmp_ne_u32_e64 s[4:5], 0, v13
	v_lshlrev_b32_e32 v16, 16, v13
	v_add_u32_e32 v17, 64, v181
	v_or_b32_e32 v16, v16, v17
	v_mbcnt_lo_u32_b32 v17, s4, 0
	v_mbcnt_hi_u32_b32 v17, s5, v17
	v_add_u32_e32 v17, s25, v17
	v_lshl_add_u32 v17, v17, 2, s46
	v_add_u32_e32 v17, 0x4000, v17
	v_add_u32_e32 v18, 0x4400, v199
	s_bcnt1_i32_b64 s9, s[4:5]
	v_cndmask_b32_e64 v17, v18, v17, s[4:5]
	s_add_i32 s25, s25, s9
	ds_write_b32 v17, v16
	v_cmp_ne_u32_e64 s[4:5], 0, v14
	v_lshlrev_b32_e32 v16, 16, v14
	v_add_u32_e32 v17, 128, v181
	v_or_b32_e32 v16, v16, v17
	v_mbcnt_lo_u32_b32 v17, s4, 0
	v_mbcnt_hi_u32_b32 v17, s5, v17
	v_add_u32_e32 v17, s25, v17
	v_lshl_add_u32 v17, v17, 2, s46
	v_add_u32_e32 v17, 0x4000, v17
	v_add_u32_e32 v18, 0x4400, v199
	s_bcnt1_i32_b64 s9, s[4:5]
	v_cndmask_b32_e64 v17, v18, v17, s[4:5]
	s_add_i32 s25, s25, s9
	ds_write_b32 v17, v16
	v_cmp_ne_u32_e64 s[4:5], 0, v15
	v_lshlrev_b32_e32 v16, 16, v15
	v_add_u32_e32 v17, 192, v181
	v_or_b32_e32 v16, v16, v17
	v_mbcnt_lo_u32_b32 v17, s4, 0
	v_mbcnt_hi_u32_b32 v17, s5, v17
	v_add_u32_e32 v17, s25, v17
	v_lshl_add_u32 v17, v17, 2, s46
	v_add_u32_e32 v17, 0x4000, v17
	v_add_u32_e32 v18, 0x4400, v199
	s_bcnt1_i32_b64 s9, s[4:5]
	v_cndmask_b32_e64 v17, v18, v17, s[4:5]
	s_add_i32 s25, s25, s9
	ds_write_b32 v17, v16
	s_waitcnt vmcnt(0)
	v_lshlrev_b32_e32 v245, 16, v100
	v_and_b32_e32 v246, 0xffff0000, v100
	v_mul_f32_e32 v245, 0x41000000, v245
	v_mul_f32_e32 v246, 0x41000000, v246
	v_lshlrev_b32_e32 v248, 16, v101
	v_and_b32_e32 v249, 0xffff0000, v101
	v_cvt_pk_fp8_f32 v164, v245, v246
	v_mul_f32_e32 v248, 0x41000000, v248
	v_mul_f32_e32 v249, 0x41000000, v249
	s_nop 0
	v_cvt_pk_fp8_f32 v164, v248, v249 op_sel:[0,0,1]
	v_lshlrev_b32_e32 v245, 16, v102
	v_and_b32_e32 v246, 0xffff0000, v102
	v_mul_f32_e32 v245, 0x41000000, v245
	v_mul_f32_e32 v246, 0x41000000, v246
	v_lshlrev_b32_e32 v248, 16, v103
	v_and_b32_e32 v249, 0xffff0000, v103
	v_cvt_pk_fp8_f32 v165, v245, v246
	v_mul_f32_e32 v248, 0x41000000, v248
	v_mul_f32_e32 v249, 0x41000000, v249
	s_nop 0
	v_cvt_pk_fp8_f32 v165, v248, v249 op_sel:[0,0,1]
	v_lshlrev_b32_e32 v245, 16, v104
	v_and_b32_e32 v246, 0xffff0000, v104
	v_mul_f32_e32 v245, 0x41000000, v245
	v_mul_f32_e32 v246, 0x41000000, v246
	v_lshlrev_b32_e32 v248, 16, v105
	v_and_b32_e32 v249, 0xffff0000, v105
	v_cvt_pk_fp8_f32 v166, v245, v246
	v_mul_f32_e32 v248, 0x41000000, v248
	v_mul_f32_e32 v249, 0x41000000, v249
	s_nop 0
	v_cvt_pk_fp8_f32 v166, v248, v249 op_sel:[0,0,1]
	v_lshlrev_b32_e32 v245, 16, v106
	v_and_b32_e32 v246, 0xffff0000, v106
	v_mul_f32_e32 v245, 0x41000000, v245
	v_mul_f32_e32 v246, 0x41000000, v246
	v_lshlrev_b32_e32 v248, 16, v107
	v_and_b32_e32 v249, 0xffff0000, v107
	v_cvt_pk_fp8_f32 v167, v245, v246
	v_mul_f32_e32 v248, 0x41000000, v248
	v_mul_f32_e32 v249, 0x41000000, v249
	s_nop 0
	v_cvt_pk_fp8_f32 v167, v248, v249 op_sel:[0,0,1]
	v_lshlrev_b32_e32 v245, 16, v108
	v_and_b32_e32 v246, 0xffff0000, v108
	v_mul_f32_e32 v245, 0x41000000, v245
	v_mul_f32_e32 v246, 0x41000000, v246
	v_lshlrev_b32_e32 v248, 16, v109
	v_and_b32_e32 v249, 0xffff0000, v109
	v_cvt_pk_fp8_f32 v168, v245, v246
	v_mul_f32_e32 v248, 0x41000000, v248
	v_mul_f32_e32 v249, 0x41000000, v249
	s_nop 0
	v_cvt_pk_fp8_f32 v168, v248, v249 op_sel:[0,0,1]
	v_lshlrev_b32_e32 v245, 16, v110
	v_and_b32_e32 v246, 0xffff0000, v110
	v_mul_f32_e32 v245, 0x41000000, v245
	v_mul_f32_e32 v246, 0x41000000, v246
	v_lshlrev_b32_e32 v248, 16, v111
	v_and_b32_e32 v249, 0xffff0000, v111
	v_cvt_pk_fp8_f32 v169, v245, v246
	v_mul_f32_e32 v248, 0x41000000, v248
	v_mul_f32_e32 v249, 0x41000000, v249
	s_nop 0
	v_cvt_pk_fp8_f32 v169, v248, v249 op_sel:[0,0,1]
	v_lshlrev_b32_e32 v245, 16, v112
	v_and_b32_e32 v246, 0xffff0000, v112
	v_mul_f32_e32 v245, 0x41000000, v245
	v_mul_f32_e32 v246, 0x41000000, v246
	v_lshlrev_b32_e32 v248, 16, v113
	v_and_b32_e32 v249, 0xffff0000, v113
	v_cvt_pk_fp8_f32 v170, v245, v246
	v_mul_f32_e32 v248, 0x41000000, v248
	v_mul_f32_e32 v249, 0x41000000, v249
	s_nop 0
	v_cvt_pk_fp8_f32 v170, v248, v249 op_sel:[0,0,1]
	v_lshlrev_b32_e32 v245, 16, v114
	v_and_b32_e32 v246, 0xffff0000, v114
	v_mul_f32_e32 v245, 0x41000000, v245
	v_mul_f32_e32 v246, 0x41000000, v246
	v_lshlrev_b32_e32 v248, 16, v115
	v_and_b32_e32 v249, 0xffff0000, v115
	v_cvt_pk_fp8_f32 v171, v245, v246
	v_mul_f32_e32 v248, 0x41000000, v248
	v_mul_f32_e32 v249, 0x41000000, v249
	s_nop 0
	v_cvt_pk_fp8_f32 v171, v248, v249 op_sel:[0,0,1]
	v_lshlrev_b32_e32 v245, 16, v116
	v_and_b32_e32 v246, 0xffff0000, v116
	v_mul_f32_e32 v245, 0x41000000, v245
	v_mul_f32_e32 v246, 0x41000000, v246
	v_lshlrev_b32_e32 v248, 16, v117
	v_and_b32_e32 v249, 0xffff0000, v117
	v_cvt_pk_fp8_f32 v182, v245, v246
	v_mul_f32_e32 v248, 0x41000000, v248
	v_mul_f32_e32 v249, 0x41000000, v249
	s_nop 0
	v_cvt_pk_fp8_f32 v182, v248, v249 op_sel:[0,0,1]
	v_lshlrev_b32_e32 v245, 16, v118
	v_and_b32_e32 v246, 0xffff0000, v118
	v_mul_f32_e32 v245, 0x41000000, v245
	v_mul_f32_e32 v246, 0x41000000, v246
	v_lshlrev_b32_e32 v248, 16, v119
	v_and_b32_e32 v249, 0xffff0000, v119
	v_cvt_pk_fp8_f32 v183, v245, v246
	v_mul_f32_e32 v248, 0x41000000, v248
	v_mul_f32_e32 v249, 0x41000000, v249
	s_nop 0
	v_cvt_pk_fp8_f32 v183, v248, v249 op_sel:[0,0,1]
	v_lshlrev_b32_e32 v245, 16, v120
	v_and_b32_e32 v246, 0xffff0000, v120
	v_mul_f32_e32 v245, 0x41000000, v245
	v_mul_f32_e32 v246, 0x41000000, v246
	v_lshlrev_b32_e32 v248, 16, v121
	v_and_b32_e32 v249, 0xffff0000, v121
	v_cvt_pk_fp8_f32 v184, v245, v246
	v_mul_f32_e32 v248, 0x41000000, v248
	v_mul_f32_e32 v249, 0x41000000, v249
	s_nop 0
	v_cvt_pk_fp8_f32 v184, v248, v249 op_sel:[0,0,1]
	v_lshlrev_b32_e32 v245, 16, v122
	v_and_b32_e32 v246, 0xffff0000, v122
	v_mul_f32_e32 v245, 0x41000000, v245
	v_mul_f32_e32 v246, 0x41000000, v246
	v_lshlrev_b32_e32 v248, 16, v123
	v_and_b32_e32 v249, 0xffff0000, v123
	v_cvt_pk_fp8_f32 v185, v245, v246
	v_mul_f32_e32 v248, 0x41000000, v248
	v_mul_f32_e32 v249, 0x41000000, v249
	s_nop 0
	v_cvt_pk_fp8_f32 v185, v248, v249 op_sel:[0,0,1]
	v_lshlrev_b32_e32 v245, 16, v124
	v_and_b32_e32 v246, 0xffff0000, v124
	v_mul_f32_e32 v245, 0x41000000, v245
	v_mul_f32_e32 v246, 0x41000000, v246
	v_lshlrev_b32_e32 v248, 16, v125
	v_and_b32_e32 v249, 0xffff0000, v125
	v_cvt_pk_fp8_f32 v186, v245, v246
	v_mul_f32_e32 v248, 0x41000000, v248
	v_mul_f32_e32 v249, 0x41000000, v249
	s_nop 0
	v_cvt_pk_fp8_f32 v186, v248, v249 op_sel:[0,0,1]
	v_lshlrev_b32_e32 v245, 16, v126
	v_and_b32_e32 v246, 0xffff0000, v126
	v_mul_f32_e32 v245, 0x41000000, v245
	v_mul_f32_e32 v246, 0x41000000, v246
	v_lshlrev_b32_e32 v248, 16, v127
	v_and_b32_e32 v249, 0xffff0000, v127
	v_cvt_pk_fp8_f32 v187, v245, v246
	v_mul_f32_e32 v248, 0x41000000, v248
	v_mul_f32_e32 v249, 0x41000000, v249
	s_nop 0
	v_cvt_pk_fp8_f32 v187, v248, v249 op_sel:[0,0,1]
	v_lshlrev_b32_e32 v245, 16, v128
	v_and_b32_e32 v246, 0xffff0000, v128
	v_mul_f32_e32 v245, 0x41000000, v245
	v_mul_f32_e32 v246, 0x41000000, v246
	v_lshlrev_b32_e32 v248, 16, v129
	v_and_b32_e32 v249, 0xffff0000, v129
	v_cvt_pk_fp8_f32 v188, v245, v246
	v_mul_f32_e32 v248, 0x41000000, v248
	v_mul_f32_e32 v249, 0x41000000, v249
	s_nop 0
	v_cvt_pk_fp8_f32 v188, v248, v249 op_sel:[0,0,1]
	v_lshlrev_b32_e32 v245, 16, v130
	v_and_b32_e32 v246, 0xffff0000, v130
	v_mul_f32_e32 v245, 0x41000000, v245
	v_mul_f32_e32 v246, 0x41000000, v246
	v_lshlrev_b32_e32 v248, 16, v131
	v_and_b32_e32 v249, 0xffff0000, v131
	v_cvt_pk_fp8_f32 v189, v245, v246
	v_mul_f32_e32 v248, 0x41000000, v248
	v_mul_f32_e32 v249, 0x41000000, v249
	s_nop 0
	v_cvt_pk_fp8_f32 v189, v248, v249 op_sel:[0,0,1]
	v_mov_b64_e32 v[100:101], 0
	v_mov_b64_e32 v[102:103], 0
	v_mov_b64_e32 v[104:105], 0
	v_mov_b64_e32 v[106:107], 0
	v_mov_b64_e32 v[108:109], 0
	v_mov_b64_e32 v[110:111], 0
	v_mov_b64_e32 v[112:113], 0
	v_mov_b64_e32 v[114:115], 0
	v_mov_b32_e32 v190, 0
	v_mov_b32_e32 v194, 0
	v_mov_b64_e32 v[116:117], 0
	v_mov_b64_e32 v[118:119], 0
	v_mov_b64_e32 v[120:121], 0
	v_mov_b64_e32 v[122:123], 0
	v_mov_b64_e32 v[124:125], 0
	v_mov_b64_e32 v[126:127], 0
	v_mov_b64_e32 v[128:129], 0
	v_mov_b64_e32 v[130:131], 0
	v_mov_b32_e32 v191, 0
	v_mov_b32_e32 v195, 0
	v_mov_b64_e32 v[132:133], 0
	v_mov_b64_e32 v[134:135], 0
	v_mov_b64_e32 v[136:137], 0
	v_mov_b64_e32 v[138:139], 0
	v_mov_b64_e32 v[140:141], 0
	v_mov_b64_e32 v[142:143], 0
	v_mov_b64_e32 v[144:145], 0
	v_mov_b64_e32 v[146:147], 0
	v_mov_b32_e32 v192, 0
	v_mov_b32_e32 v196, 0
	v_mov_b64_e32 v[148:149], 0
	v_mov_b64_e32 v[150:151], 0
	v_mov_b64_e32 v[152:153], 0
	v_mov_b64_e32 v[154:155], 0
	v_mov_b64_e32 v[156:157], 0
	v_mov_b64_e32 v[158:159], 0
	v_mov_b64_e32 v[160:161], 0
	v_mov_b64_e32 v[162:163], 0
	v_mov_b32_e32 v193, 0
	v_mov_b32_e32 v197, 0
	v_mov_b32_e32 v77, 0xff800000
	v_mov_b32_e32 v78, 0xff800000
	s_waitcnt lgkmcnt(0)
	s_mov_b32 s35, 0
	s_lshl_b32 s9, s35, 2
	s_add_i32 s9, s9, s46
	v_mov_b32_e32 v76, s9
	ds_read_b32 v76, v76 offset:16384
	s_add_i32 s50, s25, -1
	s_min_i32 s50, s50, 1
	s_waitcnt lgkmcnt(0)
	v_readfirstlane_b32 s9, v76
	s_and_b32 s38, s9, 0xffff
	s_lshr_b32 s48, s9, 16
	s_lshl_b32 s9, s50, 2
	s_add_i32 s9, s9, s46
	v_mov_b32_e32 v76, s9
	ds_read_b32 v76, v76 offset:16384
	s_lshl_b32 s29, s38, 12
	s_add_u32 s30, s40, s29
	s_addc_u32 s31, s41, 0
	global_load_dwordx4 v[2:5], v79, s[30:31]
	global_load_dwordx4 v[6:9], v79, s[30:31] offset:1024
	global_load_dwordx4 v[12:15], v79, s[30:31] offset:2048
	global_load_dwordx4 v[16:19], v79, s[30:31] offset:3072
	s_lshl_b32 s29, s38, 12
	s_add_u32 s30, s62, s29
	s_addc_u32 s31, s63, 0
	global_load_dwordx4 v[36:39], v79, s[30:31]
	global_load_dwordx4 v[40:43], v79, s[30:31] offset:1024
	global_load_dwordx4 v[44:47], v79, s[30:31] offset:2048
	global_load_dwordx4 v[48:51], v79, s[30:31] offset:3072
	s_waitcnt lgkmcnt(0)
	v_readfirstlane_b32 s9, v76
	s_and_b32 s27, s9, 0xffff
	s_lshr_b32 s8, s9, 16
	v_readfirstlane_b32 s83, v1
	s_bitcmp1_b32 s83, 8
	s_cbranch_scc0 .Lbm3_nostag
	s_sleep 4
.Lbm3_nostag:
.Lbm3_blkA:
	s_lshl_b32 s29, s27, 12
	s_add_u32 s30, s40, s29
	s_addc_u32 s31, s41, 0
	global_load_dwordx4 v[20:23], v79, s[30:31]
	global_load_dwordx4 v[24:27], v79, s[30:31] offset:1024
	global_load_dwordx4 v[28:31], v79, s[30:31] offset:2048
	global_load_dwordx4 v[32:35], v79, s[30:31] offset:3072
	s_lshl_b32 s29, s27, 12
	s_add_u32 s30, s62, s29
	s_addc_u32 s31, s63, 0
	global_load_dwordx4 v[52:55], v79, s[30:31]
	global_load_dwordx4 v[56:59], v79, s[30:31] offset:1024
	global_load_dwordx4 v[60:63], v79, s[30:31] offset:2048
	global_load_dwordx4 v[64:67], v79, s[30:31] offset:3072
	s_add_i32 s50, s35, 2
	s_add_i32 s9, s25, -1
	s_min_i32 s50, s50, s9
	s_lshl_b32 s9, s50, 2
	s_add_i32 s9, s9, s46
	v_mov_b32_e32 v76, s9
	ds_read_b32 v76, v76 offset:16384
	s_cmp_ge_i32 s38, s21
	s_cselect_b32 s50, 1, 0
	s_bfe_u32 s29, s48, 0x40000
	s_cmp_eq_u32 s29, 0
	s_cbranch_scc1 .Lbm3_Ag0_skip
	s_waitcnt vmcnt(12)
	v_mfma_f32_16x16x32_fp8_fp8 v[84:87], v[2:3], v[164:165], 0
	v_mfma_f32_16x16x32_fp8_fp8 v[88:91], v[6:7], v[164:165], 0
	v_mfma_f32_16x16x32_fp8_fp8 v[92:95], v[12:13], v[164:165], 0
	v_mfma_f32_16x16x32_fp8_fp8 v[96:99], v[16:17], v[164:165], 0
	v_mfma_f32_16x16x32_fp8_fp8 v[84:87], v[4:5], v[166:167], v[84:87]
	v_mfma_f32_16x16x32_fp8_fp8 v[88:91], v[8:9], v[166:167], v[88:91]
	v_mfma_f32_16x16x32_fp8_fp8 v[92:95], v[14:15], v[166:167], v[92:95]
	v_mfma_f32_16x16x32_fp8_fp8 v[96:99], v[18:19], v[166:167], v[96:99]
	v_and_b32_e32 v199, s29, v244
	s_cmp_eq_u32 s50, 1
	v_cmp_ne_u32_e32 vcc, 0, v199
	s_cbranch_scc1 .Lbm3_Ag0_near
	v_add_f32_e32 v200, v81, v190
	v_cndmask_b32_e32 v200, v77, v200, vcc
	v_pk_fma_f32 v[84:85], v[84:85], s[10:11], v[200:201] op_sel_hi:[1,1,0]
	v_pk_fma_f32 v[86:87], v[86:87], s[10:11], v[200:201] op_sel_hi:[1,1,0]
	v_pk_fma_f32 v[88:89], v[88:89], s[10:11], v[200:201] op_sel_hi:[1,1,0]
	v_pk_fma_f32 v[90:91], v[90:91], s[10:11], v[200:201] op_sel_hi:[1,1,0]
	v_pk_fma_f32 v[92:93], v[92:93], s[10:11], v[200:201] op_sel_hi:[1,1,0]
	v_pk_fma_f32 v[94:95], v[94:95], s[10:11], v[200:201] op_sel_hi:[1,1,0]
	v_pk_fma_f32 v[96:97], v[96:97], s[10:11], v[200:201] op_sel_hi:[1,1,0]
	v_pk_fma_f32 v[98:99], v[98:99], s[10:11], v[200:201] op_sel_hi:[1,1,0]
